# dilated attention: T5 bias lookups batched (padded LDS table, ds_read2 issued in S phase, branch-free mask)
# speedup vs baseline: 1.0042x; 1.0042x over previous
.LBB0_790:
	s_mov_b64 s[0:1], s[78:79]
	s_load_dword s0, s[0:1], 0xa8
	s_waitcnt lgkmcnt(0)
	s_cmp_gt_i32 s0, 8
	s_cbranch_scc1 .LBB0_1110
	s_mov_b64 s[0:1], s[78:79]
	s_load_dword s0, s[0:1], 0xac
	s_waitcnt lgkmcnt(0)
	s_cmp_lt_i32 s0, 9
	s_cbranch_scc1 .LBB0_1110
	s_mov_b64 s[0:1], s[78:79]
	s_load_dwordx2 s[6:7], s[0:1], 0xa0
	s_mov_b32 s33, -1
	s_mov_b32 s0, -1
	s_cmpk_gt_i32 s80, 0xbff
	s_cbranch_scc1 .LBB0_1106
	s_waitcnt lgkmcnt(0)
	s_add_u32 s48, s6, 0x46a00000
	s_addc_u32 s49, s7, 0
	s_add_u32 s50, s6, 0x5aa00000
	s_addc_u32 s51, s7, 0
	s_add_u32 s52, s6, 0x200000
	s_mov_b32 s1, s80
	s_addc_u32 s53, s7, 0
	s_ashr_i32 s11, s1, 4
	s_mul_hi_i32 s2, s11, 0x55555556
	s_lshr_b32 s3, s2, 31
	s_add_i32 s12, s2, s3
	s_mul_i32 s2, s12, 3
	s_and_b32 s10, s1, 15
	s_sub_i32 s13, s11, s2
	s_cmp_eq_u32 s13, 0
	s_cselect_b64 s[2:3], -1, 0
	s_cmp_eq_u32 s13, 1
	s_cselect_b64 s[4:5], -1, 0
	s_bfe_u32 s14, s1, 0x20002
	s_and_b64 s[8:9], s[4:5], exec
	s_cselect_b32 s14, s14, s10
	s_and_b64 s[8:9], s[2:3], exec
	v_mbcnt_lo_u32_b32 v0, s0, 0
	s_cselect_b32 s14, 0, s14
	s_and_b32 s1, s1, 3
	v_mbcnt_hi_u32_b32 v19, s0, v0
	s_and_b64 s[8:9], s[4:5], exec
	v_add_u32_e32 v16, s93, v19
	s_cselect_b32 s1, s1, 0
	s_and_b64 s[8:9], s[2:3], exec
	v_bfe_i32 v2, v16, 27, 1
	s_mul_hi_i32 s8, s11, 0x2aaaaaab
	v_lshlrev_b32_e32 v1, 4, v16
	v_lshrrev_b32_e32 v2, 22, v2
	s_cselect_b32 s1, s10, s1
	s_lshr_b32 s9, s8, 31
	s_ashr_i32 s8, s8, 2
	v_add_u32_e32 v2, v1, v2
	s_add_i32 s8, s8, s9
	v_and_b32_e32 v2, 0xfffffc00, v2
	s_mov_b32 s54, 0xa000
	s_and_b64 s[10:11], s[4:5], exec
	v_sub_u32_e32 v2, v1, v2
	s_cselect_b32 s9, s54, 0x28000
	s_and_b64 s[10:11], s[2:3], exec
	v_ashrrev_i32_e32 v17, 31, v16
	v_lshrrev_b32_e32 v3, 4, v2
	s_cselect_b32 s15, 0x2800, s9
	s_ashr_i32 s9, s8, 31
	v_lshrrev_b32_e32 v0, 26, v17
	v_bitop3_b32 v2, v3, v2, 32 bitop3:0x6c
	s_lshl_b64 s[8:9], s[8:9], 11
	s_lshl_b32 s16, s1, 7
	v_add_u32_e32 v0, v16, v0
	v_ashrrev_i32_e32 v4, 31, v2
	s_and_b64 s[10:11], s[4:5], exec
	v_ashrrev_i32_e32 v0, 6, v0
	v_lshrrev_b32_e32 v4, 26, v4
	s_cselect_b32 s17, 2, 4
	s_and_b64 s[10:11], s[2:3], exec
	v_lshlrev_b32_e32 v3, 3, v0
	v_add_u32_e32 v4, v2, v4
	s_cselect_b32 s10, 0, s17
	v_and_b32_e32 v3, -16, v3
	v_ashrrev_i32_e32 v5, 6, v4
	s_lshl_b32 s10, s16, s10
	v_add_u32_e32 v96, v5, v3
	v_and_b32_e32 v3, 0xc0, v4
	s_add_u32 s8, s8, s10
	v_lshlrev_b32_e32 v0, 5, v0
	v_sub_u32_e32 v2, v2, v3
	v_mov_b32_e32 v97, 1
	s_addc_u32 s9, s9, 0
	s_or_b32 s8, s8, s14
	v_and_b32_e32 v0, 32, v0
	v_ashrrev_i16_sdwa v2, v97, sext(v2) dst_sel:DWORD dst_unused:UNUSED_PAD src0_sel:DWORD src1_sel:BYTE_0
	v_add_u32_e32 v1, 0x2000, v1
	s_mulk_i32 s9, 0x5000
	s_mul_hi_u32 s10, s8, 0x5000
	v_add_u32_sdwa v0, v0, sext(v2) dst_sel:DWORD dst_unused:UNUSED_PAD src0_sel:DWORD src1_sel:WORD_0
	v_ashrrev_i32_e32 v2, 31, v1
	s_add_i32 s10, s10, s9
	s_mulk_i32 s8, 0x5000
	v_lshrrev_b32_e32 v2, 22, v2
	s_add_u32 s11, s48, s8
	v_add_u32_e32 v2, v1, v2
	s_addc_u32 s10, s49, s10
	s_lshl_b32 s8, s13, 10
	v_ashrrev_i32_e32 v2, 10, v2
	s_ashr_i32 s9, s8, 31
	v_mul_i32_i24_e32 v3, 0x400, v2
	s_lshl_b64 s[8:9], s[8:9], 1
	v_sub_u32_e32 v1, v1, v3
	s_add_u32 s8, s11, s8
	v_lshrrev_b32_e32 v3, 4, v1
	s_addc_u32 s9, s10, s9
	s_lshl_b32 s10, s12, 8
	v_bitop3_b32 v1, v3, v1, 32 bitop3:0x6c
	s_and_b32 s10, s10, 0x700
	v_ashrrev_i32_e32 v4, 31, v1
	s_add_u32 s10, s8, s10
	v_lshrrev_b32_e32 v4, 26, v4
	s_addc_u32 s11, s9, 0
	v_lshlrev_b32_e32 v3, 3, v2
	v_add_u32_e32 v4, v1, v4
	s_mov_b32 s55, 0xff600000
	s_and_b64 s[4:5], s[4:5], exec
	v_and_b32_e32 v3, -16, v3
	v_ashrrev_i32_e32 v5, 6, v4
	s_cselect_b32 s4, s55, 0xfd800000
	s_and_b64 s[2:3], s[2:3], exec
	v_add_u32_e32 v98, v5, v3
	v_and_b32_e32 v3, 0xc0, v4
	s_cselect_b32 s2, 0xffd80000, s4
	v_lshlrev_b32_e32 v2, 5, v2
	v_sub_u32_e32 v1, v1, v3
	s_add_u32 s2, s10, s2
	v_and_b32_e32 v2, 32, v2
	v_ashrrev_i16_sdwa v1, v97, sext(v1) dst_sel:DWORD dst_unused:UNUSED_PAD src0_sel:DWORD src1_sel:BYTE_0
	s_addc_u32 s3, s11, -1
	v_and_b32_e32 v81, 15, v19
	v_add_u32_sdwa v2, v2, sext(v1) dst_sel:DWORD dst_unused:UNUSED_PAD src0_sel:DWORD src1_sel:WORD_0
	v_lshlrev_b32_e32 v1, 3, v19
	v_lshlrev_b32_e32 v4, 2, v19
	s_cmp_eq_u32 s1, 0
	s_mov_b32 s4, s81
	v_and_b32_e32 v25, 24, v1
	v_lshlrev_b32_e32 v1, 6, v81
	v_and_b32_e32 v3, 48, v19
	v_and_b32_e32 v4, 32, v4
	s_cselect_b32 s12, 0x80, 0
	v_bitop3_b32 v26, v1, v4, v3 bitop3:0x36
	s_lshl_b32 s4, s4, 10
	v_max_i32_e32 v1, s12, v96
	s_add_i32 s13, s4, 0
	v_mad_u64_u32 v[4:5], s[4:5], s15, v1, 0
	v_ashrrev_i32_e32 v1, 31, v0
	v_lshl_add_u64 v[4:5], v[4:5], 1, s[2:3]
	v_lshlrev_b64 v[82:83], 1, v[0:1]
	v_max_i32_e32 v3, s12, v98
	v_lshl_add_u64 v[0:1], v[4:5], 0, v[82:83]
	v_mad_u64_u32 v[4:5], s[4:5], s15, v3, 0
	v_ashrrev_i32_e32 v3, 31, v2
	s_mov_b32 m0, s13
	v_lshl_add_u64 v[4:5], v[4:5], 1, s[2:3]
	v_lshlrev_b64 v[84:85], 1, v[2:3]
	global_load_lds_dwordx4 v[0:1], off
	v_lshl_add_u64 v[2:3], v[4:5], 0, v[84:85]
	s_add_i32 m0, s13, 0x2000
	s_mov_b64 s[8:9], 0x80
	global_load_lds_dwordx4 v[2:3], off
	s_add_i32 m0, s13, 0x4000
	v_lshl_add_u64 v[0:1], v[0:1], 0, s[8:9]
	global_load_lds_dwordx4 v[0:1], off
	v_lshl_add_u64 v[0:1], v[2:3], 0, s[8:9]
	s_add_i32 m0, s13, 0x6000
	v_add_u32_e32 v100, 0x80, v96
	global_load_lds_dwordx4 v[0:1], off
	v_max_i32_e32 v0, s12, v100
	v_add_u32_e32 v101, 0x80, v98
	v_mad_u64_u32 v[0:1], s[4:5], s15, v0, 0
	v_max_i32_e32 v2, s12, v101
	v_lshl_add_u64 v[0:1], v[0:1], 1, s[2:3]
	v_mad_u64_u32 v[2:3], s[4:5], s15, v2, 0
	s_add_i32 m0, s13, 0x8000
	v_lshl_add_u64 v[0:1], v[0:1], 0, v[82:83]
	v_lshl_add_u64 v[2:3], v[2:3], 1, s[2:3]
	global_load_lds_dwordx4 v[0:1], off
	v_lshl_add_u64 v[2:3], v[2:3], 0, v[84:85]
	s_add_i32 m0, s13, 0xa000
	v_lshl_add_u64 v[0:1], v[0:1], 0, s[8:9]
	global_load_lds_dwordx4 v[2:3], off
	s_add_i32 m0, s13, 0xc000
	v_lshl_or_b32 v86, s81, 4, v81
	global_load_lds_dwordx4 v[0:1], off
	v_lshl_add_u64 v[0:1], v[2:3], 0, s[8:9]
	s_add_i32 m0, s13, 0xe000
	v_mov_b32_e32 v89, 0
	global_load_lds_dwordx4 v[0:1], off
	v_mad_u64_u32 v[0:1], s[2:3], s15, v86, 0
	v_lshl_add_u64 v[0:1], v[0:1], 1, s[10:11]
	v_and_b32_e32 v88, 0x70, v19
	v_lshrrev_b32_e32 v99, 4, v19
	v_lshl_add_u64 v[0:1], v[0:1], 0, v[88:89]
	s_mov_b64 s[10:11], 0x3000
	s_movk_i32 s2, 0x3000
	v_bfe_u32 v6, v19, 2, 2
	v_lshlrev_b32_e32 v80, 2, v99
	v_lshlrev_b32_e32 v7, 4, v19
	v_lshl_add_u64 v[20:21], v[0:1], 0, s[10:11]
	v_add_co_u32_e32 v22, vcc, s2, v0
	v_or_b32_e32 v24, v80, v6
	v_and_or_b32 v27, v80, 4, v6
	v_and_b32_e32 v28, 0x400, v7
	v_addc_co_u32_e32 v23, vcc, 0, v1, vcc
	global_load_dwordx4 v[0:3], v[20:21], off offset:64
	global_load_dwordx4 v[4:7], v[20:21], off offset:128
	global_load_dwordx4 v[8:11], v[22:23], off
	global_load_dwordx4 v[12:15], v[20:21], off offset:192
	v_lshlrev_b32_e32 v20, 8, v24
	s_add_i32 s4, 0, 0x20000
	s_add_i32 s57, 0, 0x10000
	s_movk_i32 s0, 0xc0
	s_movk_i32 s1, 0x80
	s_movk_i32 s56, 0x81
	v_lshl_add_u32 v102, v16, 2, s4
	v_add3_u32 v20, v25, s57, v20
	v_cmp_gt_u32_e64 s[4:5], 16, v19
	v_lshlrev_b32_e32 v19, 5, v27
	v_cmp_gt_i32_e64 s[2:3], s56, v16
	v_xad_u32 v171, v19, s1, v20
	v_xad_u32 v173, v19, s0, v20
	v_lshl_add_u64 v[16:17], v[16:17], 2, s[6:7]
	s_mov_b64 s[0:1], 0x120000
	v_lshlrev_b32_e32 v18, 3, v99
	s_movk_i32 s12, 0x60
	s_movk_i32 s13, 0xa0
	s_movk_i32 s14, 0xe0
	v_lshl_add_u64 v[90:91], v[16:17], 0, s[0:1]
	v_mbcnt_lo_u32_b32 v16, -1, 0
	v_mov_b32_e32 v87, v89
	v_add3_u32 v103, 0, v26, v28
	v_or_b32_e32 v104, 1, v80
	v_or_b32_e32 v105, 2, v80
	v_or_b32_e32 v106, 3, v80
	v_add_u32_e32 v107, 16, v80
	v_add_u32_e32 v108, 17, v80
	v_add_u32_e32 v109, 18, v80
	v_add_u32_e32 v110, 19, v80
	v_or_b32_e32 v111, 32, v80
	v_or_b32_e32 v112, 33, v80
	v_or_b32_e32 v113, 34, v80
	v_or_b32_e32 v114, 35, v80
	v_add_u32_e32 v115, 48, v80
	v_add_u32_e32 v116, 49, v80
	v_add_u32_e32 v117, 50, v80
	v_add_u32_e32 v118, 51, v80
	v_or_b32_e32 v119, 64, v80
	v_or_b32_e32 v120, 0x41, v80
	v_or_b32_e32 v121, 0x42, v80
	v_or_b32_e32 v122, 0x43, v80
	v_add_u32_e32 v123, 0x50, v80
	v_add_u32_e32 v124, 0x51, v80
	v_add_u32_e32 v125, 0x52, v80
	v_add_u32_e32 v126, 0x53, v80
	v_or_b32_e32 v127, 0x60, v80
	v_or_b32_e32 v128, 0x61, v80
	v_or_b32_e32 v129, 0x62, v80
	v_or_b32_e32 v130, 0x63, v80
	v_add_u32_e32 v131, 0x70, v80
	v_add_u32_e32 v132, 0x71, v80
	v_add_u32_e32 v133, 0x72, v80
	v_add_u32_e32 v134, 0x73, v80
	v_or_b32_e32 v136, 0x81, v80
	v_or_b32_e32 v137, 0x82, v80
	v_or_b32_e32 v138, 0x83, v80
	v_add_u32_e32 v139, 0x90, v80
	v_add_u32_e32 v140, 0x91, v80
	v_add_u32_e32 v141, 0x92, v80
	v_add_u32_e32 v142, 0x93, v80
	v_or_b32_e32 v143, 0xa0, v80
	v_or_b32_e32 v144, 0xa1, v80
	v_or_b32_e32 v145, 0xa2, v80
	v_or_b32_e32 v146, 0xa3, v80
	v_add_u32_e32 v147, 0xb0, v80
	v_add_u32_e32 v148, 0xb1, v80
	v_add_u32_e32 v149, 0xb2, v80
	v_add_u32_e32 v150, 0xb3, v80
	v_or_b32_e32 v151, 0xc0, v80
	v_or_b32_e32 v152, 0xc1, v80
	v_or_b32_e32 v153, 0xc2, v80
	v_or_b32_e32 v154, 0xc3, v80
	v_add_u32_e32 v155, 0xd0, v80
	v_add_u32_e32 v156, 0xd1, v80
	v_add_u32_e32 v157, 0xd2, v80
	v_add_u32_e32 v158, 0xd3, v80
	v_or_b32_e32 v159, 0xe0, v80
	v_or_b32_e32 v160, 0xe1, v80
	v_or_b32_e32 v161, 0xe2, v80
	v_or_b32_e32 v162, 0xe3, v80
	v_add_u32_e32 v163, 0xf0, v80
	v_mov_b32_e32 v164, 0xff61b1e6
	v_sub_u32_e32 v166, v81, v80
	v_lshlrev_b32_e64 v165, 4, s81
	v_add_u32_e32 v166, v166, v165
	v_mov_b32_e32 v165, 0x1fe74
	v_lshl_add_u32 v166, v166, 2, v165
	v_add_u32_e32 v167, v20, v19
	v_xad_u32 v168, v19, 32, v20
	v_xad_u32 v169, v19, 64, v20
	v_xad_u32 v170, v19, s12, v20
	v_xad_u32 v172, v19, s13, v20
	v_xad_u32 v174, v19, s14, v20
	s_mov_b32 s58, 0xff61b1e6
	s_mov_b32 s59, 0xfe967699
	v_lshlrev_b32_e32 v92, 1, v18
	s_movk_i32 s60, 0x7fff
	s_mov_b32 s61, 0xffff0000
	v_lshlrev_b32_e32 v94, 1, v80
	s_movk_i32 s62, 0x180
	s_mov_b32 s63, 0x800000
	s_mov_b32 s64, 0x3f317217
	s_mov_b32 s65, 0x7f800000
	v_mbcnt_hi_u32_b32 v175, -1, v16
	s_mov_b32 s66, s80
	s_branch .LBB0_795

.LBB0_795:
	s_mov_b32 s14, s66
	s_ashr_i32 s15, s14, 4
	s_mul_hi_i32 s0, s15, 0x55555556
	s_lshr_b32 s1, s0, 31
	s_add_i32 s0, s0, s1
	s_mul_i32 s1, s0, 3
	s_sub_i32 s13, s15, s1
	s_and_b32 s12, s0, 7
	v_mov_b32_e32 v16, 0xff61b1e6
	v_cmp_gt_u32_e32 vcc, 0x20280, v102
	s_and_saveexec_b64 s[0:1], vcc
	ds_write_b32 v102, v16
	s_mov_b64 exec, s[0:1]
	v_add_u32_e32 v17, 0xfffdffc0, v102
	v_cmp_gt_u32_e32 vcc, 0x204, v17
	s_and_saveexec_b64 s[0:1], vcc
	s_cbranch_execz .LBB0_797
	s_lshl_b32 s16, s13, 3
	s_or_b32 s16, s16, s12
	s_mulk_i32 s16, 0x81
	s_ashr_i32 s17, s16, 31
	v_lshl_add_u64 v[16:17], s[16:17], 2, v[90:91]
	global_load_dword v16, v[16:17], off offset:-64
	s_waitcnt vmcnt(0)
	ds_write_b32 v102, v16
.LBB0_797:
	s_or_b64 exec, exec, s[0:1]
	s_mul_hi_i32 s0, s15, 0x2aaaaaab
	s_lshr_b32 s1, s0, 31
	s_ashr_i32 s0, s0, 2
	s_add_i32 s0, s0, s1
	s_ashr_i32 s1, s0, 31
	s_and_b32 s16, s14, 15
	s_bfe_u32 s17, s14, 0x20002
	s_and_b32 s14, s14, 3
	s_lshl_b64 s[0:1], s[0:1], 11
	s_cmp_eq_u32 s13, 1
	s_cselect_b32 s15, s17, s16
	s_cselect_b32 s14, s14, 0
	s_cselect_b32 s17, s54, 0x28000
	s_cselect_b32 s18, 2, 4
	s_cselect_b32 s19, s55, 0xfd800000
	s_cmp_eq_u32 s13, 0
	s_cselect_b32 s14, s16, s14
	s_cselect_b32 s15, 0, s15
	s_cselect_b32 s16, 0x2800, s17
	s_cselect_b32 s17, 0, s18
	s_cselect_b32 s18, 0xffd80000, s19
	s_lshl_b32 s19, s14, 7
	s_lshl_b32 s17, s19, s17
	s_add_u32 s0, s0, s17
	s_addc_u32 s1, s1, 0
	s_or_b32 s0, s0, s15
	s_mulk_i32 s1, 0x5000
	s_mul_hi_u32 s15, s0, 0x5000
	s_add_i32 s15, s15, s1
	s_mulk_i32 s0, 0x5000
	s_add_u32 s17, s48, s0
	s_addc_u32 s15, s49, s15
	s_lshl_b32 s0, s13, 10
	s_ashr_i32 s1, s0, 31
	s_lshl_b64 s[0:1], s[0:1], 1
	s_add_u32 s0, s17, s0
	s_addc_u32 s1, s15, s1
	s_lshl_b32 s12, s12, 8
	s_add_u32 s0, s0, s12
	s_addc_u32 s1, s1, 0
	s_add_u32 s0, s0, s18
	s_addc_u32 s1, s1, -1
	s_add_u32 s0, s0, 0x1800
	s_addc_u32 s1, s1, 0
	s_cmp_eq_u32 s14, 0
	s_mov_b32 s15, s81
	s_cselect_b32 s14, 0x80, 0
	s_waitcnt vmcnt(0) lgkmcnt(0)
	s_waitcnt vmcnt(0)
	s_barrier
	s_add_i32 s17, s15, 8
	v_lshl_add_u32 v16, s15, 2, v99
	v_max_i32_e32 v17, s14, v16
	v_lshlrev_b32_e32 v16, 1, v16
	v_bitop3_b32 v18, v16, v81, 14 bitop3:0x6c
	v_mad_u64_u32 v[16:17], s[12:13], s16, v17, 0
	v_lshl_add_u64 v[16:17], v[16:17], 1, s[0:1]
	v_lshlrev_b32_e32 v88, 4, v18
	s_lshl_b32 s12, s15, 10
	v_lshl_add_u64 v[16:17], v[16:17], 0, v[88:89]
	s_add_i32 m0, s57, s12
	s_mov_b32 s68, s81
	global_load_lds_dwordx4 v[16:17], off
	v_lshl_add_u32 v16, s17, 2, v99
	v_max_i32_e32 v17, s14, v16
	v_lshlrev_b32_e32 v16, 1, v16
	v_bitop3_b32 v18, v16, v81, 14 bitop3:0x6c
	v_mad_u64_u32 v[16:17], s[12:13], s16, v17, 0
	v_lshl_add_u64 v[16:17], v[16:17], 1, s[0:1]
	v_lshlrev_b32_e32 v88, 4, v18
	s_lshl_b32 s12, s17, 10
	v_lshl_add_u64 v[16:17], v[16:17], 0, v[88:89]
	s_add_i32 m0, s57, s12
	s_add_i32 s17, s15, 16
	global_load_lds_dwordx4 v[16:17], off
	v_lshl_add_u32 v16, s17, 2, v99
	v_max_i32_e32 v17, s14, v16
	v_lshlrev_b32_e32 v16, 1, v16
	v_bitop3_b32 v18, v16, v81, 14 bitop3:0x6c
	v_mad_u64_u32 v[16:17], s[12:13], s16, v17, 0
	v_lshl_add_u64 v[16:17], v[16:17], 1, s[0:1]
	v_lshlrev_b32_e32 v88, 4, v18
	s_lshl_b32 s12, s17, 10
	v_lshl_add_u64 v[16:17], v[16:17], 0, v[88:89]
	s_add_i32 m0, s57, s12
	s_add_i32 s17, s15, 24
	global_load_lds_dwordx4 v[16:17], off
	v_lshl_add_u32 v16, s17, 2, v99
	v_max_i32_e32 v17, s14, v16
	v_lshlrev_b32_e32 v16, 1, v16
	v_bitop3_b32 v18, v16, v81, 14 bitop3:0x6c
	v_mad_u64_u32 v[16:17], s[12:13], s16, v17, 0
	v_lshl_add_u64 v[16:17], v[16:17], 1, s[0:1]
	v_lshlrev_b32_e32 v88, 4, v18
	s_lshl_b32 s12, s17, 10
	v_lshl_add_u64 v[16:17], v[16:17], 0, v[88:89]
	s_add_i32 m0, s57, s12
	s_add_i32 s17, s15, 32
	global_load_lds_dwordx4 v[16:17], off
	v_lshl_add_u32 v16, s17, 2, v99
	v_max_i32_e32 v17, s14, v16
	v_lshlrev_b32_e32 v16, 1, v16
	v_bitop3_b32 v18, v16, v81, 14 bitop3:0x6c
	v_mad_u64_u32 v[16:17], s[12:13], s16, v17, 0
	v_lshl_add_u64 v[16:17], v[16:17], 1, s[0:1]
	v_lshlrev_b32_e32 v88, 4, v18
	s_lshl_b32 s12, s17, 10
	v_lshl_add_u64 v[16:17], v[16:17], 0, v[88:89]
	s_add_i32 m0, s57, s12
	s_add_i32 s17, s15, 40
	global_load_lds_dwordx4 v[16:17], off
	v_lshl_add_u32 v16, s17, 2, v99
	v_max_i32_e32 v17, s14, v16
	v_lshlrev_b32_e32 v16, 1, v16
	v_bitop3_b32 v18, v16, v81, 14 bitop3:0x6c
	v_mad_u64_u32 v[16:17], s[12:13], s16, v17, 0
	v_lshl_add_u64 v[16:17], v[16:17], 1, s[0:1]
	v_lshlrev_b32_e32 v88, 4, v18
	s_lshl_b32 s12, s17, 10
	v_lshl_add_u64 v[16:17], v[16:17], 0, v[88:89]
	s_add_i32 m0, s57, s12
	s_add_i32 s17, s15, 48
	global_load_lds_dwordx4 v[16:17], off
	v_lshl_add_u32 v16, s17, 2, v99
	v_max_i32_e32 v17, s14, v16
	v_lshlrev_b32_e32 v16, 1, v16
	v_bitop3_b32 v18, v16, v81, 14 bitop3:0x6c
	v_mad_u64_u32 v[16:17], s[12:13], s16, v17, 0
	v_lshl_add_u64 v[16:17], v[16:17], 1, s[0:1]
	v_lshlrev_b32_e32 v88, 4, v18
	s_lshl_b32 s12, s17, 10
	v_lshl_add_u64 v[16:17], v[16:17], 0, v[88:89]
	s_add_i32 m0, s57, s12
	s_add_i32 s15, s15, 56
	global_load_lds_dwordx4 v[16:17], off
	v_lshl_add_u32 v16, s15, 2, v99
	v_max_i32_e32 v17, s14, v16
	v_lshlrev_b32_e32 v16, 1, v16
	v_bitop3_b32 v18, v16, v81, 14 bitop3:0x6c
	v_mad_u64_u32 v[16:17], s[12:13], s16, v17, 0
	v_lshl_add_u64 v[16:17], v[16:17], 1, s[0:1]
	v_lshlrev_b32_e32 v88, 4, v18
	s_lshl_b32 s0, s15, 10
	v_lshl_add_u64 v[16:17], v[16:17], 0, v[88:89]
	s_add_i32 m0, s57, s0
	s_mov_b32 s0, s66
	global_load_lds_dwordx4 v[16:17], off
	s_ashr_i32 s12, s0, 4
	s_mul_hi_i32 s13, s12, 0x55555556
	s_lshr_b32 s14, s13, 31
	s_add_i32 s13, s13, s14
	s_mul_i32 s13, s13, 3
	s_and_b32 s1, s0, 15
	s_sub_i32 s12, s12, s13
	s_and_b32 s0, s0, 3
	s_cmp_eq_u32 s12, 1
	s_cselect_b32 s0, s0, 0
	s_cmp_eq_u32 s12, 0
	s_cselect_b32 s0, s1, s0
	s_cmp_eq_u32 s0, 0
	s_cselect_b32 s67, 0x80, 0
	s_lshr_b32 s0, s67, 4
	s_max_i32 s0, s68, s0
	s_cmp_eq_u32 s0, 0
	s_cselect_b64 s[44:45], -1, 0
	s_cmp_lg_u32 s0, 0
	s_cselect_b64 s[12:13], -1, 0
	s_cmp_lt_i32 s68, -8
	s_cselect_b64 s[14:15], -1, 0
	s_or_b64 s[12:13], s[14:15], s[12:13]
	v_mov_b32_e32 v72, 0
	s_and_b64 vcc, exec, s[12:13]
	v_mov_b32_e32 v76, 0
	v_mov_b32_e32 v77, 0
	v_mov_b32_e32 v78, 0
	v_mov_b32_e32 v79, 0
	s_cbranch_vccnz .LBB0_799
	ds_read_b128 v[16:19], v103
	ds_read_b128 v[20:23], v103 offset:1024
	ds_read_b128 v[24:27], v103 offset:16384
	s_waitcnt lgkmcnt(0)
	v_mfma_f32_16x16x32_bf16 v[16:19], v[16:19], v[8:11], 0
	v_mfma_f32_16x16x32_bf16 v[16:19], v[20:23], v[0:3], v[16:19]
	ds_read_b128 v[20:23], v103 offset:17408
	v_mfma_f32_16x16x32_bf16 v[16:19], v[24:27], v[4:7], v[16:19]
	s_waitcnt lgkmcnt(0)
	ds_read2_b32 v[104:105], v166 offset0:243 offset1:242
	ds_read2_b32 v[106:107], v166 offset0:241 offset1:240
	v_mfma_f32_16x16x32_bf16 v[76:79], v[20:23], v[12:15], v[16:19]
.LBB0_799:
	s_cmp_lt_u32 s0, 2
	s_cselect_b64 s[42:43], -1, 0
	s_cmp_gt_u32 s0, 1
	s_cselect_b64 s[12:13], -1, 0
	s_cmp_lt_i32 s68, -7
	s_cselect_b64 s[14:15], -1, 0
	s_or_b64 s[12:13], s[14:15], s[12:13]
	s_and_b64 vcc, exec, s[12:13]
	v_mov_b32_e32 v73, 0
	v_mov_b32_e32 v74, 0
	v_mov_b32_e32 v75, 0
	s_cbranch_vccnz .LBB0_801
	ds_read_b128 v[16:19], v103 offset:2048
	ds_read_b128 v[20:23], v103 offset:3072
	ds_read_b128 v[24:27], v103 offset:18432
	s_waitcnt lgkmcnt(0)
	v_mfma_f32_16x16x32_bf16 v[16:19], v[16:19], v[8:11], 0
	v_mfma_f32_16x16x32_bf16 v[16:19], v[20:23], v[0:3], v[16:19]
	ds_read_b128 v[20:23], v103 offset:19456
	v_mfma_f32_16x16x32_bf16 v[16:19], v[24:27], v[4:7], v[16:19]
	s_waitcnt lgkmcnt(0)
	ds_read2_b32 v[108:109], v166 offset0:227 offset1:226
	ds_read2_b32 v[110:111], v166 offset0:225 offset1:224
	v_mfma_f32_16x16x32_bf16 v[72:75], v[20:23], v[12:15], v[16:19]
.LBB0_801:
	s_cmp_lt_u32 s0, 3
	s_cselect_b64 s[40:41], -1, 0
	s_cmp_gt_u32 s0, 2
	s_cselect_b64 s[12:13], -1, 0
	s_cmp_lt_i32 s68, -6
	s_cselect_b64 s[14:15], -1, 0
	s_or_b64 s[12:13], s[14:15], s[12:13]
	v_mov_b32_e32 v64, 0
	s_and_b64 vcc, exec, s[12:13]
	v_mov_b32_e32 v68, 0
	v_mov_b32_e32 v69, 0
	v_mov_b32_e32 v70, 0
	v_mov_b32_e32 v71, 0
	s_cbranch_vccnz .LBB0_803
	ds_read_b128 v[16:19], v103 offset:4096
	ds_read_b128 v[20:23], v103 offset:5120
	ds_read_b128 v[24:27], v103 offset:20480
	s_waitcnt lgkmcnt(0)
	v_mfma_f32_16x16x32_bf16 v[16:19], v[16:19], v[8:11], 0
	v_mfma_f32_16x16x32_bf16 v[16:19], v[20:23], v[0:3], v[16:19]
	ds_read_b128 v[20:23], v103 offset:21504
	v_mfma_f32_16x16x32_bf16 v[16:19], v[24:27], v[4:7], v[16:19]
	s_waitcnt lgkmcnt(0)
	ds_read2_b32 v[112:113], v166 offset0:211 offset1:210
	ds_read2_b32 v[114:115], v166 offset0:209 offset1:208
	v_mfma_f32_16x16x32_bf16 v[68:71], v[20:23], v[12:15], v[16:19]
.LBB0_803:
	s_cmp_lt_u32 s0, 4
	s_cselect_b64 s[38:39], -1, 0
	s_cmp_gt_u32 s0, 3
	s_cselect_b64 s[12:13], -1, 0
	s_cmp_lt_i32 s68, -5
	s_cselect_b64 s[14:15], -1, 0
	s_or_b64 s[12:13], s[14:15], s[12:13]
	s_and_b64 vcc, exec, s[12:13]
	v_mov_b32_e32 v65, 0
	v_mov_b32_e32 v66, 0
	v_mov_b32_e32 v67, 0
	s_cbranch_vccnz .LBB0_805
	ds_read_b128 v[16:19], v103 offset:6144
	ds_read_b128 v[20:23], v103 offset:7168
	ds_read_b128 v[24:27], v103 offset:22528
	s_waitcnt lgkmcnt(0)
	v_mfma_f32_16x16x32_bf16 v[16:19], v[16:19], v[8:11], 0
	v_mfma_f32_16x16x32_bf16 v[16:19], v[20:23], v[0:3], v[16:19]
	ds_read_b128 v[20:23], v103 offset:23552
	v_mfma_f32_16x16x32_bf16 v[16:19], v[24:27], v[4:7], v[16:19]
	s_waitcnt lgkmcnt(0)
	ds_read2_b32 v[116:117], v166 offset0:195 offset1:194
	ds_read2_b32 v[118:119], v166 offset0:193 offset1:192
	v_mfma_f32_16x16x32_bf16 v[64:67], v[20:23], v[12:15], v[16:19]
.LBB0_805:
	s_cmp_lt_u32 s0, 5
	s_cselect_b64 s[36:37], -1, 0
	s_cmp_gt_u32 s0, 4
	s_cselect_b64 s[12:13], -1, 0
	s_cmp_lt_i32 s68, -4
	s_cselect_b64 s[14:15], -1, 0
	s_or_b64 s[12:13], s[14:15], s[12:13]
	v_mov_b32_e32 v56, 0
	s_and_b64 vcc, exec, s[12:13]
	v_mov_b32_e32 v60, 0
	v_mov_b32_e32 v61, 0
	v_mov_b32_e32 v62, 0
	v_mov_b32_e32 v63, 0
	s_cbranch_vccnz .LBB0_807
	ds_read_b128 v[16:19], v103 offset:8192
	ds_read_b128 v[20:23], v103 offset:9216
	ds_read_b128 v[24:27], v103 offset:24576
	s_waitcnt lgkmcnt(0)
	v_mfma_f32_16x16x32_bf16 v[16:19], v[16:19], v[8:11], 0
	v_mfma_f32_16x16x32_bf16 v[16:19], v[20:23], v[0:3], v[16:19]
	ds_read_b128 v[20:23], v103 offset:25600
	v_mfma_f32_16x16x32_bf16 v[16:19], v[24:27], v[4:7], v[16:19]
	s_waitcnt lgkmcnt(0)
	ds_read2_b32 v[120:121], v166 offset0:179 offset1:178
	ds_read2_b32 v[122:123], v166 offset0:177 offset1:176
	v_mfma_f32_16x16x32_bf16 v[60:63], v[20:23], v[12:15], v[16:19]
.LBB0_807:
	s_cmp_lt_u32 s0, 6
	s_cselect_b64 s[34:35], -1, 0
	s_cmp_gt_u32 s0, 5
	s_cselect_b64 s[12:13], -1, 0
	s_cmp_lt_i32 s68, -3
	s_cselect_b64 s[14:15], -1, 0
	s_or_b64 s[12:13], s[14:15], s[12:13]
	s_and_b64 vcc, exec, s[12:13]
	v_mov_b32_e32 v57, 0
	v_mov_b32_e32 v58, 0
	v_mov_b32_e32 v59, 0
	s_cbranch_vccnz .LBB0_809
	ds_read_b128 v[16:19], v103 offset:10240
	ds_read_b128 v[20:23], v103 offset:11264
	ds_read_b128 v[24:27], v103 offset:26624
	s_waitcnt lgkmcnt(0)
	v_mfma_f32_16x16x32_bf16 v[16:19], v[16:19], v[8:11], 0
	v_mfma_f32_16x16x32_bf16 v[16:19], v[20:23], v[0:3], v[16:19]
	ds_read_b128 v[20:23], v103 offset:27648
	v_mfma_f32_16x16x32_bf16 v[16:19], v[24:27], v[4:7], v[16:19]
	s_waitcnt lgkmcnt(0)
	ds_read2_b32 v[124:125], v166 offset0:163 offset1:162
	ds_read2_b32 v[126:127], v166 offset0:161 offset1:160
	v_mfma_f32_16x16x32_bf16 v[56:59], v[20:23], v[12:15], v[16:19]
.LBB0_809:
	s_cmp_lt_u32 s0, 7
	s_cselect_b64 s[30:31], -1, 0
	s_cmp_gt_u32 s0, 6
	s_cselect_b64 s[12:13], -1, 0
	s_cmp_lt_i32 s68, -2
	s_cselect_b64 s[14:15], -1, 0
	s_or_b64 s[12:13], s[14:15], s[12:13]
	v_mov_b32_e32 v48, 0
	s_and_b64 vcc, exec, s[12:13]
	v_mov_b32_e32 v52, 0
	v_mov_b32_e32 v53, 0
	v_mov_b32_e32 v54, 0
	v_mov_b32_e32 v55, 0
	s_cbranch_vccnz .LBB0_811
	ds_read_b128 v[16:19], v103 offset:12288
	ds_read_b128 v[20:23], v103 offset:13312
	ds_read_b128 v[24:27], v103 offset:28672
	s_waitcnt lgkmcnt(0)
	v_mfma_f32_16x16x32_bf16 v[16:19], v[16:19], v[8:11], 0
	v_mfma_f32_16x16x32_bf16 v[16:19], v[20:23], v[0:3], v[16:19]
	ds_read_b128 v[20:23], v103 offset:29696
	v_mfma_f32_16x16x32_bf16 v[16:19], v[24:27], v[4:7], v[16:19]
	s_waitcnt lgkmcnt(0)
	ds_read2_b32 v[128:129], v166 offset0:147 offset1:146
	ds_read2_b32 v[130:131], v166 offset0:145 offset1:144
	v_mfma_f32_16x16x32_bf16 v[52:55], v[20:23], v[12:15], v[16:19]
.LBB0_811:
	s_cmp_lt_u32 s0, 8
	s_cselect_b64 s[28:29], -1, 0
	s_cmp_gt_u32 s0, 7
	s_cselect_b64 s[12:13], -1, 0
	s_cmp_lt_i32 s68, -1
	s_cselect_b64 s[14:15], -1, 0
	s_or_b64 s[12:13], s[14:15], s[12:13]
	s_and_b64 vcc, exec, s[12:13]
	v_mov_b32_e32 v49, 0
	v_mov_b32_e32 v50, 0
	v_mov_b32_e32 v51, 0
	s_cbranch_vccnz .LBB0_813
	ds_read_b128 v[16:19], v103 offset:14336
	ds_read_b128 v[20:23], v103 offset:15360
	ds_read_b128 v[24:27], v103 offset:30720
	s_waitcnt lgkmcnt(0)
	v_mfma_f32_16x16x32_bf16 v[16:19], v[16:19], v[8:11], 0
	v_mfma_f32_16x16x32_bf16 v[16:19], v[20:23], v[0:3], v[16:19]
	ds_read_b128 v[20:23], v103 offset:31744
	v_mfma_f32_16x16x32_bf16 v[16:19], v[24:27], v[4:7], v[16:19]
	s_waitcnt lgkmcnt(0)
	ds_read2_b32 v[132:133], v166 offset0:131 offset1:130
	ds_read2_b32 v[136:137], v166 offset0:129 offset1:128
	v_mfma_f32_16x16x32_bf16 v[48:51], v[20:23], v[12:15], v[16:19]
.LBB0_813:
	s_cmp_lt_u32 s0, 9
	s_cselect_b64 s[26:27], -1, 0
	s_cmp_gt_u32 s0, 8
	s_cselect_b64 s[12:13], -1, 0
	s_cmp_lt_i32 s68, 0
	s_cselect_b64 s[14:15], -1, 0
	s_or_b64 s[12:13], s[14:15], s[12:13]
	v_mov_b32_e32 v40, 0
	s_and_b64 vcc, exec, s[12:13]
	v_mov_b32_e32 v44, 0
	v_mov_b32_e32 v45, 0
	v_mov_b32_e32 v46, 0
	v_mov_b32_e32 v47, 0
	s_cbranch_vccnz .LBB0_815
	ds_read_b128 v[16:19], v103 offset:32768
	ds_read_b128 v[20:23], v103 offset:33792
	ds_read_b128 v[24:27], v103 offset:49152
	s_waitcnt lgkmcnt(0)
	v_mfma_f32_16x16x32_bf16 v[16:19], v[16:19], v[8:11], 0
	v_mfma_f32_16x16x32_bf16 v[16:19], v[20:23], v[0:3], v[16:19]
	ds_read_b128 v[20:23], v103 offset:50176
	v_mfma_f32_16x16x32_bf16 v[16:19], v[24:27], v[4:7], v[16:19]
	s_waitcnt lgkmcnt(0)
	ds_read2_b32 v[138:139], v166 offset0:115 offset1:114
	ds_read2_b32 v[140:141], v166 offset0:113 offset1:112
	v_mfma_f32_16x16x32_bf16 v[44:47], v[20:23], v[12:15], v[16:19]
.LBB0_815:
	s_cmp_lt_u32 s0, 10
	s_cselect_b64 s[24:25], -1, 0
	s_cmp_gt_u32 s0, 9
	s_cselect_b64 s[12:13], -1, 0
	s_cmp_lt_i32 s68, 1
	s_cselect_b64 s[14:15], -1, 0
	s_or_b64 s[12:13], s[14:15], s[12:13]
	s_and_b64 vcc, exec, s[12:13]
	v_mov_b32_e32 v41, 0
	v_mov_b32_e32 v42, 0
	v_mov_b32_e32 v43, 0
	s_cbranch_vccnz .LBB0_817
	ds_read_b128 v[16:19], v103 offset:34816
	ds_read_b128 v[20:23], v103 offset:35840
	ds_read_b128 v[24:27], v103 offset:51200
	s_waitcnt lgkmcnt(0)
	v_mfma_f32_16x16x32_bf16 v[16:19], v[16:19], v[8:11], 0
	v_mfma_f32_16x16x32_bf16 v[16:19], v[20:23], v[0:3], v[16:19]
	ds_read_b128 v[20:23], v103 offset:52224
	v_mfma_f32_16x16x32_bf16 v[16:19], v[24:27], v[4:7], v[16:19]
	s_waitcnt lgkmcnt(0)
	ds_read2_b32 v[104:105], v166 offset0:99 offset1:98
	ds_read2_b32 v[106:107], v166 offset0:97 offset1:96
	v_mfma_f32_16x16x32_bf16 v[40:43], v[20:23], v[12:15], v[16:19]
.LBB0_817:
	s_cmp_lt_u32 s0, 11
	s_cselect_b64 s[22:23], -1, 0
	s_cmp_gt_u32 s0, 10
	s_cselect_b64 s[12:13], -1, 0
	s_cmp_lt_i32 s68, 2
	s_cselect_b64 s[14:15], -1, 0
	s_or_b64 s[12:13], s[14:15], s[12:13]
	v_mov_b32_e32 v32, 0
	s_and_b64 vcc, exec, s[12:13]
	v_mov_b32_e32 v36, 0
	v_mov_b32_e32 v37, 0
	v_mov_b32_e32 v38, 0
	v_mov_b32_e32 v39, 0
	s_cbranch_vccnz .LBB0_819
	ds_read_b128 v[16:19], v103 offset:36864
	ds_read_b128 v[20:23], v103 offset:37888
	ds_read_b128 v[24:27], v103 offset:53248
	s_waitcnt lgkmcnt(0)
	v_mfma_f32_16x16x32_bf16 v[16:19], v[16:19], v[8:11], 0
	v_mfma_f32_16x16x32_bf16 v[16:19], v[20:23], v[0:3], v[16:19]
	ds_read_b128 v[20:23], v103 offset:54272
	v_mfma_f32_16x16x32_bf16 v[16:19], v[24:27], v[4:7], v[16:19]
	s_waitcnt lgkmcnt(0)
	ds_read2_b32 v[108:109], v166 offset0:83 offset1:82
	ds_read2_b32 v[110:111], v166 offset0:81 offset1:80
	v_mfma_f32_16x16x32_bf16 v[36:39], v[20:23], v[12:15], v[16:19]
.LBB0_819:
	s_cmp_lt_u32 s0, 12
	s_cselect_b64 s[20:21], -1, 0
	s_cmp_gt_u32 s0, 11
	s_cselect_b64 s[12:13], -1, 0
	s_cmp_lt_i32 s68, 3
	s_cselect_b64 s[14:15], -1, 0
	s_or_b64 s[12:13], s[14:15], s[12:13]
	s_and_b64 vcc, exec, s[12:13]
	v_mov_b32_e32 v33, 0
	v_mov_b32_e32 v34, 0
	v_mov_b32_e32 v35, 0
	s_cbranch_vccnz .LBB0_821
	ds_read_b128 v[16:19], v103 offset:38912
	ds_read_b128 v[20:23], v103 offset:39936
	ds_read_b128 v[24:27], v103 offset:55296
	s_waitcnt lgkmcnt(0)
	v_mfma_f32_16x16x32_bf16 v[16:19], v[16:19], v[8:11], 0
	v_mfma_f32_16x16x32_bf16 v[16:19], v[20:23], v[0:3], v[16:19]
	ds_read_b128 v[20:23], v103 offset:56320
	v_mfma_f32_16x16x32_bf16 v[16:19], v[24:27], v[4:7], v[16:19]
	s_waitcnt lgkmcnt(0)
	ds_read2_b32 v[112:113], v166 offset0:67 offset1:66
	ds_read2_b32 v[114:115], v166 offset0:65 offset1:64
	v_mfma_f32_16x16x32_bf16 v[32:35], v[20:23], v[12:15], v[16:19]
.LBB0_821:
	s_cmp_lt_u32 s0, 13
	s_cselect_b64 s[18:19], -1, 0
	s_cmp_gt_u32 s0, 12
	s_cselect_b64 s[12:13], -1, 0
	s_cmp_lt_i32 s68, 4
	s_cselect_b64 s[14:15], -1, 0
	s_or_b64 s[12:13], s[14:15], s[12:13]
	v_mov_b32_e32 v24, 0
	s_and_b64 vcc, exec, s[12:13]
	v_mov_b32_e32 v28, 0
	v_mov_b32_e32 v29, 0
	v_mov_b32_e32 v30, 0
	v_mov_b32_e32 v31, 0
	s_cbranch_vccnz .LBB0_823
	ds_read_b128 v[16:19], v103 offset:40960
	ds_read_b128 v[20:23], v103 offset:41984
	ds_read_b128 v[26:29], v103 offset:57344
	s_waitcnt lgkmcnt(0)
	v_mfma_f32_16x16x32_bf16 v[16:19], v[16:19], v[8:11], 0
	v_mfma_f32_16x16x32_bf16 v[16:19], v[20:23], v[0:3], v[16:19]
	ds_read_b128 v[20:23], v103 offset:58368
	v_mfma_f32_16x16x32_bf16 v[16:19], v[26:29], v[4:7], v[16:19]
	s_waitcnt lgkmcnt(0)
	ds_read2_b32 v[116:117], v166 offset0:51 offset1:50
	ds_read2_b32 v[118:119], v166 offset0:49 offset1:48
	v_mfma_f32_16x16x32_bf16 v[28:31], v[20:23], v[12:15], v[16:19]
.LBB0_823:
	s_cmp_lt_u32 s0, 14
	s_cselect_b64 s[16:17], -1, 0
	s_cmp_gt_u32 s0, 13
	s_cselect_b64 s[12:13], -1, 0
	s_cmp_lt_i32 s68, 5
	s_cselect_b64 s[14:15], -1, 0
	s_or_b64 s[12:13], s[14:15], s[12:13]
	s_and_b64 vcc, exec, s[12:13]
	v_mov_b32_e32 v25, 0
	v_mov_b32_e32 v26, 0
	v_mov_b32_e32 v27, 0
	s_cbranch_vccnz .LBB0_825
	ds_read_b128 v[16:19], v103 offset:43008
	ds_read_b128 v[20:23], v103 offset:44032
	ds_read_b128 v[24:27], v103 offset:59392
	s_waitcnt lgkmcnt(0)
	v_mfma_f32_16x16x32_bf16 v[16:19], v[16:19], v[8:11], 0
	v_mfma_f32_16x16x32_bf16 v[16:19], v[20:23], v[0:3], v[16:19]
	ds_read_b128 v[20:23], v103 offset:60416
	v_mfma_f32_16x16x32_bf16 v[16:19], v[24:27], v[4:7], v[16:19]
	s_waitcnt lgkmcnt(0)
	ds_read2_b32 v[120:121], v166 offset0:35 offset1:34
	ds_read2_b32 v[122:123], v166 offset0:33 offset1:32
	v_mfma_f32_16x16x32_bf16 v[24:27], v[20:23], v[12:15], v[16:19]
.LBB0_825:
	s_cmp_lt_u32 s0, 15
	s_cselect_b64 s[14:15], -1, 0
	s_cmp_gt_u32 s0, 14
	s_cselect_b64 s[12:13], -1, 0
	s_cmp_lt_i32 s68, 6
	s_cselect_b64 s[46:47], -1, 0
	s_or_b64 s[12:13], s[46:47], s[12:13]
	v_mov_b32_e32 v16, 0
	s_and_b64 vcc, exec, s[12:13]
	v_mov_b32_e32 v20, 0
	v_mov_b32_e32 v21, 0
	v_mov_b32_e32 v22, 0
	v_mov_b32_e32 v23, 0
	s_cbranch_vccnz .LBB0_827
	ds_read_b128 v[18:21], v103 offset:45056
	ds_read_b128 v[178:181], v103 offset:46080
	ds_read_b128 v[182:185], v103 offset:61440
	s_waitcnt lgkmcnt(0)
	v_mfma_f32_16x16x32_bf16 v[18:21], v[18:21], v[8:11], 0
	v_mfma_f32_16x16x32_bf16 v[18:21], v[178:181], v[0:3], v[18:21]
	ds_read_b128 v[178:181], v103 offset:62464
	v_mfma_f32_16x16x32_bf16 v[18:21], v[182:185], v[4:7], v[18:21]
	s_waitcnt lgkmcnt(0)
	ds_read2_b32 v[124:125], v166 offset0:19 offset1:18
	ds_read2_b32 v[126:127], v166 offset0:17 offset1:16
	v_mfma_f32_16x16x32_bf16 v[20:23], v[178:181], v[12:15], v[18:21]
.LBB0_827:
	s_cmp_lt_u32 s0, 16
	s_cselect_b64 s[12:13], -1, 0
	s_cmp_gt_u32 s0, 15
	s_cselect_b64 s[0:1], -1, 0
	s_cmp_lt_i32 s68, 7
	s_cselect_b64 s[46:47], -1, 0
	s_or_b64 s[0:1], s[46:47], s[0:1]
	s_and_b64 vcc, exec, s[0:1]
	v_mov_b32_e32 v17, 0
	v_mov_b32_e32 v18, 0
	v_mov_b32_e32 v19, 0
	s_cbranch_vccnz .LBB0_829
	ds_read_b128 v[16:19], v103 offset:47104
	ds_read_b128 v[178:181], v103 offset:48128
	ds_read_b128 v[182:185], v103 offset:63488
	s_waitcnt lgkmcnt(0)
	v_mfma_f32_16x16x32_bf16 v[16:19], v[16:19], v[8:11], 0
	v_mfma_f32_16x16x32_bf16 v[16:19], v[178:181], v[0:3], v[16:19]
	ds_read_b128 v[178:181], v103 offset:64512
	v_mfma_f32_16x16x32_bf16 v[16:19], v[182:185], v[4:7], v[16:19]
	s_waitcnt lgkmcnt(0)
	ds_read2_b32 v[128:129], v166 offset0:3 offset1:2
	ds_read2_b32 v[130:131], v166 offset0:1 offset1:0
	v_mfma_f32_16x16x32_bf16 v[16:19], v[178:181], v[12:15], v[16:19]
.LBB0_829:
	s_waitcnt lgkmcnt(0)
	s_lshr_b32 s12, s67, 4
	s_max_i32 s12, s12, s81
	s_add_i32 s13, s81, 9
	s_sub_i32 s13, s13, s12
	s_bfm_b32 s12, s13, s12
	s_bitcmp1_b32 s12, 0
	s_cselect_b64 s[16:17], -1, 0
	v_fmac_f32_e32 v104, 0x3db504f3, v76
	v_fmac_f32_e32 v105, 0x3db504f3, v77
	v_fmac_f32_e32 v106, 0x3db504f3, v78
	v_fmac_f32_e32 v107, 0x3db504f3, v79
	v_cndmask_b32_e64 v93, v164, v104, s[16:17]
	v_cndmask_b32_e64 v88, v164, v105, s[16:17]
	v_cndmask_b32_e64 v77, v164, v106, s[16:17]
	v_cndmask_b32_e64 v76, v164, v107, s[16:17]
	s_bitcmp1_b32 s12, 1
	s_cselect_b64 s[16:17], -1, 0
	v_fmac_f32_e32 v108, 0x3db504f3, v72
	v_fmac_f32_e32 v109, 0x3db504f3, v73
	v_fmac_f32_e32 v110, 0x3db504f3, v74
	v_fmac_f32_e32 v111, 0x3db504f3, v75
	v_cndmask_b32_e64 v79, v164, v108, s[16:17]
	v_cndmask_b32_e64 v78, v164, v109, s[16:17]
	v_cndmask_b32_e64 v73, v164, v110, s[16:17]
	v_cndmask_b32_e64 v72, v164, v111, s[16:17]
	s_bitcmp1_b32 s12, 2
	s_cselect_b64 s[16:17], -1, 0
	v_fmac_f32_e32 v112, 0x3db504f3, v68
	v_fmac_f32_e32 v113, 0x3db504f3, v69
	v_fmac_f32_e32 v114, 0x3db504f3, v70
	v_fmac_f32_e32 v115, 0x3db504f3, v71
	v_cndmask_b32_e64 v75, v164, v112, s[16:17]
	v_cndmask_b32_e64 v74, v164, v113, s[16:17]
	v_cndmask_b32_e64 v69, v164, v114, s[16:17]
	v_cndmask_b32_e64 v68, v164, v115, s[16:17]
	s_bitcmp1_b32 s12, 3
	s_cselect_b64 s[16:17], -1, 0
	v_fmac_f32_e32 v116, 0x3db504f3, v64
	v_fmac_f32_e32 v117, 0x3db504f3, v65
	v_fmac_f32_e32 v118, 0x3db504f3, v66
	v_fmac_f32_e32 v119, 0x3db504f3, v67
	v_cndmask_b32_e64 v71, v164, v116, s[16:17]
	v_cndmask_b32_e64 v70, v164, v117, s[16:17]
	v_cndmask_b32_e64 v65, v164, v118, s[16:17]
	v_cndmask_b32_e64 v64, v164, v119, s[16:17]
	s_bitcmp1_b32 s12, 4
	s_cselect_b64 s[16:17], -1, 0
	v_fmac_f32_e32 v120, 0x3db504f3, v60
	v_fmac_f32_e32 v121, 0x3db504f3, v61
	v_fmac_f32_e32 v122, 0x3db504f3, v62
	v_fmac_f32_e32 v123, 0x3db504f3, v63
	v_cndmask_b32_e64 v67, v164, v120, s[16:17]
	v_cndmask_b32_e64 v66, v164, v121, s[16:17]
	v_cndmask_b32_e64 v61, v164, v122, s[16:17]
	v_cndmask_b32_e64 v60, v164, v123, s[16:17]
	s_bitcmp1_b32 s12, 5
	s_cselect_b64 s[16:17], -1, 0
	v_fmac_f32_e32 v124, 0x3db504f3, v56
	v_fmac_f32_e32 v125, 0x3db504f3, v57
	v_fmac_f32_e32 v126, 0x3db504f3, v58
	v_fmac_f32_e32 v127, 0x3db504f3, v59
	v_cndmask_b32_e64 v63, v164, v124, s[16:17]
	v_cndmask_b32_e64 v62, v164, v125, s[16:17]
	v_cndmask_b32_e64 v57, v164, v126, s[16:17]
	v_cndmask_b32_e64 v56, v164, v127, s[16:17]
	s_bitcmp1_b32 s12, 6
	s_cselect_b64 s[16:17], -1, 0
	v_fmac_f32_e32 v128, 0x3db504f3, v52
	v_fmac_f32_e32 v129, 0x3db504f3, v53
	v_fmac_f32_e32 v130, 0x3db504f3, v54
	v_fmac_f32_e32 v131, 0x3db504f3, v55
	v_cndmask_b32_e64 v59, v164, v128, s[16:17]
	v_cndmask_b32_e64 v58, v164, v129, s[16:17]
	v_cndmask_b32_e64 v177, v164, v130, s[16:17]
	v_cndmask_b32_e64 v53, v164, v131, s[16:17]
	s_bitcmp1_b32 s12, 7
	s_cselect_b64 s[16:17], -1, 0
	v_fmac_f32_e32 v132, 0x3db504f3, v48
	v_fmac_f32_e32 v133, 0x3db504f3, v49
	v_fmac_f32_e32 v136, 0x3db504f3, v50
	v_fmac_f32_e32 v137, 0x3db504f3, v51
	v_cndmask_b32_e64 v55, v164, v132, s[16:17]
	v_cndmask_b32_e64 v54, v164, v133, s[16:17]
	v_cndmask_b32_e64 v49, v164, v136, s[16:17]
	v_cndmask_b32_e64 v48, v164, v137, s[16:17]
	s_bitcmp1_b32 s12, 8
	s_cselect_b64 s[16:17], -1, 0
	v_fmac_f32_e32 v138, 0x3db504f3, v44
	v_fmac_f32_e32 v139, 0x3db504f3, v45
	v_fmac_f32_e32 v140, 0x3db504f3, v46
	v_fmac_f32_e32 v141, 0x3db504f3, v47
	v_cndmask_b32_e64 v51, v164, v138, s[16:17]
	v_cndmask_b32_e64 v50, v164, v139, s[16:17]
	v_cndmask_b32_e64 v45, v164, v140, s[16:17]
	v_cndmask_b32_e64 v44, v164, v141, s[16:17]
	s_bitcmp1_b32 s12, 9
	s_cselect_b64 s[16:17], -1, 0
	v_fmac_f32_e32 v104, 0x3db504f3, v40
	v_fmac_f32_e32 v105, 0x3db504f3, v41
	v_fmac_f32_e32 v106, 0x3db504f3, v42
	v_fmac_f32_e32 v107, 0x3db504f3, v43
	v_cndmask_b32_e64 v47, v164, v104, s[16:17]
	v_cndmask_b32_e64 v46, v164, v105, s[16:17]
	v_cndmask_b32_e64 v41, v164, v106, s[16:17]
	v_cndmask_b32_e64 v40, v164, v107, s[16:17]
	s_bitcmp1_b32 s12, 10
	s_cselect_b64 s[16:17], -1, 0
	v_fmac_f32_e32 v108, 0x3db504f3, v36
	v_fmac_f32_e32 v109, 0x3db504f3, v37
	v_fmac_f32_e32 v110, 0x3db504f3, v38
	v_fmac_f32_e32 v111, 0x3db504f3, v39
	v_cndmask_b32_e64 v43, v164, v108, s[16:17]
	v_cndmask_b32_e64 v42, v164, v109, s[16:17]
	v_cndmask_b32_e64 v37, v164, v110, s[16:17]
	v_cndmask_b32_e64 v36, v164, v111, s[16:17]
	s_bitcmp1_b32 s12, 11
	s_cselect_b64 s[16:17], -1, 0
	v_fmac_f32_e32 v112, 0x3db504f3, v32
	v_fmac_f32_e32 v113, 0x3db504f3, v33
	v_fmac_f32_e32 v114, 0x3db504f3, v34
	v_fmac_f32_e32 v115, 0x3db504f3, v35
	v_cndmask_b32_e64 v39, v164, v112, s[16:17]
	v_cndmask_b32_e64 v38, v164, v113, s[16:17]
	v_cndmask_b32_e64 v33, v164, v114, s[16:17]
	v_cndmask_b32_e64 v32, v164, v115, s[16:17]
	s_bitcmp1_b32 s12, 12
	s_cselect_b64 s[16:17], -1, 0
	v_fmac_f32_e32 v116, 0x3db504f3, v28
	v_fmac_f32_e32 v117, 0x3db504f3, v29
	v_fmac_f32_e32 v118, 0x3db504f3, v30
	v_fmac_f32_e32 v119, 0x3db504f3, v31
	v_cndmask_b32_e64 v35, v164, v116, s[16:17]
	v_cndmask_b32_e64 v34, v164, v117, s[16:17]
	v_cndmask_b32_e64 v29, v164, v118, s[16:17]
	v_cndmask_b32_e64 v28, v164, v119, s[16:17]
	s_bitcmp1_b32 s12, 13
	s_cselect_b64 s[16:17], -1, 0
	v_fmac_f32_e32 v120, 0x3db504f3, v24
	v_fmac_f32_e32 v121, 0x3db504f3, v25
	v_fmac_f32_e32 v122, 0x3db504f3, v26
	v_fmac_f32_e32 v123, 0x3db504f3, v27
	v_cndmask_b32_e64 v31, v164, v120, s[16:17]
	v_cndmask_b32_e64 v30, v164, v121, s[16:17]
	v_cndmask_b32_e64 v25, v164, v122, s[16:17]
	v_cndmask_b32_e64 v24, v164, v123, s[16:17]
	s_bitcmp1_b32 s12, 14
	s_cselect_b64 s[16:17], -1, 0
	v_fmac_f32_e32 v124, 0x3db504f3, v20
	v_fmac_f32_e32 v125, 0x3db504f3, v21
	v_fmac_f32_e32 v126, 0x3db504f3, v22
	v_fmac_f32_e32 v127, 0x3db504f3, v23
	v_cndmask_b32_e64 v27, v164, v124, s[16:17]
	v_cndmask_b32_e64 v26, v164, v125, s[16:17]
	v_cndmask_b32_e64 v21, v164, v126, s[16:17]
	v_cndmask_b32_e64 v20, v164, v127, s[16:17]
	s_bitcmp1_b32 s12, 15
	s_cselect_b64 s[16:17], -1, 0
	v_fmac_f32_e32 v128, 0x3db504f3, v16
	v_fmac_f32_e32 v129, 0x3db504f3, v17
	v_fmac_f32_e32 v130, 0x3db504f3, v18
	v_fmac_f32_e32 v131, 0x3db504f3, v19
	v_cndmask_b32_e64 v23, v164, v128, s[16:17]
	v_cndmask_b32_e64 v22, v164, v129, s[16:17]
	v_cndmask_b32_e64 v17, v164, v130, s[16:17]
	v_cndmask_b32_e64 v16, v164, v131, s[16:17]
